# qkv GEMM rope epilogue: the 16 sin/cos loads of a tile issued together before the last MFMAs, counted waits (bit-identical)
# baseline (speedup 1.0000x reference)
.LBB0_121:
	s_mul_hi_i32 s10, s68, 0x2aaaaaab
	s_lshr_b32 s11, s10, 31
	s_ashr_i32 s10, s10, 2
	s_add_i32 s11, s10, s11
	s_lshl_b32 s10, s11, 7
	s_mul_i32 s14, s11, 0xffffffe8
	s_mulk_i32 s11, 0xf400
	s_add_i32 s69, s68, s14
	s_add_i32 s14, s3, s11
	s_ashr_i32 s11, s10, 31
	v_readlane_b32 s72, v245, 37
	s_lshl_b64 s[28:29], s[10:11], 11
	v_readlane_b32 s84, v245, 49
	v_readlane_b32 s73, v245, 38
	v_readlane_b32 s74, v245, 39
	v_readlane_b32 s75, v245, 40
	v_readlane_b32 s76, v245, 41
	v_readlane_b32 s77, v245, 42
	v_readlane_b32 s78, v245, 43
	v_readlane_b32 s79, v245, 44
	v_readlane_b32 s80, v245, 45
	v_readlane_b32 s81, v245, 46
	v_readlane_b32 s82, v245, 47
	v_readlane_b32 s83, v245, 48
	v_readlane_b32 s85, v245, 50
	v_readlane_b32 s86, v245, 51
	v_readlane_b32 s87, v245, 52
	s_add_u32 s28, s84, s28
	s_addc_u32 s29, s85, s29
	s_ashr_i32 s15, s14, 31
	v_readlane_b32 s72, v245, 21
	s_lshl_b64 s[30:31], s[14:15], 11
	v_readlane_b32 s86, v245, 35
	v_readlane_b32 s87, v245, 36
	s_add_u32 s30, s86, s30
	s_addc_u32 s31, s87, s31
	v_readfirstlane_b32 s70, v92
	v_mov_b32_e32 v2, s31
	v_mov_b32_e32 v3, s29
	v_mov_b32_e32 v4, s30
	v_mov_b32_e32 v5, s28
	s_add_u32 s98, s28, 0x80
	s_addc_u32 s99, s29, 0
	v_lshl_add_u64 v[76:77], s[28:29], 0, v[64:65]
	s_mov_b32 m0, s70
	v_cndmask_b32_e64 v1, v2, v3, s[4:5]
	v_cndmask_b32_e64 v0, v4, v5, s[4:5]
	v_readfirstlane_b32 s71, v95
	v_readlane_b32 s78, v245, 27
	global_load_lds_dwordx4 v[76:77], off
	v_lshl_add_u64 v[78:79], v[0:1], 0, v[66:67]
	s_mov_b32 m0, s71
	v_cndmask_b32_e64 v1, v2, v3, s[6:7]
	v_cndmask_b32_e64 v0, v4, v5, s[6:7]
	v_readfirstlane_b32 s72, v96
	v_readlane_b32 s79, v245, 28
	global_load_lds_dwordx4 v[78:79], off
	v_lshl_add_u64 v[80:81], v[0:1], 0, v[68:69]
	s_mov_b32 m0, s72
	v_cndmask_b32_e64 v1, v2, v3, s[8:9]
	v_cndmask_b32_e64 v0, v4, v5, s[8:9]
	v_readfirstlane_b32 s78, v97
	v_readlane_b32 s80, v245, 29
	global_load_lds_dwordx4 v[80:81], off
	v_lshl_add_u64 v[84:85], v[0:1], 0, v[70:71]
	s_mov_b32 m0, s78
	v_readfirstlane_b32 s79, v98
	v_readlane_b32 s81, v245, 30
	global_load_lds_dwordx4 v[84:85], off
	s_add_u32 s100, s30, 0x80
	s_addc_u32 s101, s31, 0
	v_lshl_add_u64 v[86:87], s[30:31], 0, v[64:65]
	s_mov_b32 m0, s79
	v_readfirstlane_b32 s80, v99
	v_readlane_b32 s73, v245, 22
	global_load_lds_dwordx4 v[86:87], off
	v_lshl_add_u64 v[88:89], s[30:31], 0, v[66:67]
	s_mov_b32 m0, s80
	v_readfirstlane_b32 s81, v100
	global_load_lds_dwordx4 v[88:89], off
	v_lshl_add_u64 v[90:91], s[30:31], 0, v[68:69]
	s_mov_b32 m0, s81
	v_readfirstlane_b32 s73, v101
	global_load_lds_dwordx4 v[90:91], off
	v_lshl_add_u64 v[82:83], s[30:31], 0, v[70:71]
	s_mov_b32 m0, s73
	v_readfirstlane_b32 s11, v102
	global_load_lds_dwordx4 v[82:83], off
	s_mov_b32 m0, s11
	v_readfirstlane_b32 s15, v103
	s_waitcnt vmcnt(0)
	s_waitcnt vmcnt(0) lgkmcnt(0)
	s_barrier
	global_load_lds_dwordx4 v64, s[98:99]
	s_mov_b32 m0, s15
	v_readfirstlane_b32 s28, v104
	global_load_lds_dwordx4 v66, s[98:99]
	s_mov_b32 m0, s28
	v_readfirstlane_b32 s29, v105
	global_load_lds_dwordx4 v68, s[98:99]
	s_mov_b32 m0, s29
	v_readfirstlane_b32 s30, v106
	global_load_lds_dwordx4 v70, s[98:99]
	s_mov_b32 m0, s30
	v_readfirstlane_b32 s31, v107
	global_load_lds_dwordx4 v64, s[100:101]
	s_mov_b32 m0, s31
	v_readfirstlane_b32 s34, v108
	global_load_lds_dwordx4 v66, s[100:101]
	ds_read_b128 v[0:3], v111 offset:16384
	ds_read_b128 v[24:27], v111 offset:20480
	s_mov_b32 m0, s34
	v_readfirstlane_b32 s35, v109
	global_load_lds_dwordx4 v68, s[100:101]
	s_mov_b32 m0, s35
	ds_read_b128 v[16:19], v110
	global_load_lds_dwordx4 v70, s[100:101]
	s_add_u32 s98, s98, 0x80
	s_addc_u32 s99, s99, 0
	s_add_u32 s100, s100, 0x80
	s_addc_u32 s101, s101, 0
	ds_read_b128 v[20:23], v110 offset:4096
	s_waitcnt lgkmcnt(0)
	v_mfma_f32_32x32x16_bf16 v[32:47], v[0:3], v[16:19], 0
	ds_read_b128 v[118:121], v113 offset:16384
	ds_read_b128 v[122:125], v112
	ds_read_b128 v[126:129], v112 offset:4096
	s_mov_b32 m0, s70
	s_cmp_lt_i32 s69, 16
	s_cselect_b64 vcc, -1, 0
	s_cmp_gt_i32 s69, 15
	v_readlane_b32 s74, v245, 23
	v_mfma_f32_32x32x16_bf16 v[0:15], v[0:3], v[20:23], 0
	v_readlane_b32 s75, v245, 24
	v_readlane_b32 s76, v245, 25
	v_readlane_b32 s77, v245, 26
	v_readlane_b32 s82, v245, 31
	v_readlane_b32 s83, v245, 32
	v_readlane_b32 s84, v245, 33
	v_readlane_b32 s85, v245, 34
	s_waitcnt lgkmcnt(0)
	v_mfma_f32_32x32x16_bf16 v[32:47], v[118:121], v[122:125], v[32:47]
	v_mfma_f32_32x32x16_bf16 v[0:15], v[118:121], v[126:129], v[0:15]
	ds_read_b128 v[118:121], v113 offset:20480
	v_mfma_f32_32x32x16_bf16 v[48:63], v[24:27], v[16:19], 0
	v_mfma_f32_32x32x16_bf16 v[16:31], v[24:27], v[20:23], 0
	s_waitcnt lgkmcnt(0)
	v_mfma_f32_32x32x16_bf16 v[48:63], v[118:121], v[122:125], v[48:63]
	v_mfma_f32_32x32x16_bf16 v[16:31], v[118:121], v[126:129], v[16:31]
	ds_read_b128 v[118:121], v115 offset:16384
	ds_read_b128 v[122:125], v114
	ds_read_b128 v[126:129], v114 offset:4096
	s_waitcnt lgkmcnt(0)
	v_mfma_f32_32x32x16_bf16 v[32:47], v[118:121], v[122:125], v[32:47]
	v_mfma_f32_32x32x16_bf16 v[0:15], v[118:121], v[126:129], v[0:15]
	ds_read_b128 v[118:121], v115 offset:20480
	s_waitcnt lgkmcnt(0)
	v_mfma_f32_32x32x16_bf16 v[48:63], v[118:121], v[122:125], v[48:63]
	v_mfma_f32_32x32x16_bf16 v[16:31], v[118:121], v[126:129], v[16:31]
	ds_read_b128 v[118:121], v117 offset:16384
	ds_read_b128 v[122:125], v116
	ds_read_b128 v[126:129], v116 offset:4096
	s_waitcnt lgkmcnt(0)
	v_mfma_f32_32x32x16_bf16 v[32:47], v[118:121], v[122:125], v[32:47]
	v_mfma_f32_32x32x16_bf16 v[0:15], v[118:121], v[126:129], v[0:15]
	ds_read_b128 v[118:121], v117 offset:20480
	s_waitcnt vmcnt(0)
	s_waitcnt vmcnt(0) lgkmcnt(0)
	s_barrier
	v_mfma_f32_32x32x16_bf16 v[48:63], v[118:121], v[122:125], v[48:63]
	v_mfma_f32_32x32x16_bf16 v[16:31], v[118:121], v[126:129], v[16:31]
	global_load_lds_dwordx4 v64, s[98:99]
	s_mov_b32 m0, s71
	s_nop 0
	global_load_lds_dwordx4 v66, s[98:99]
	s_mov_b32 m0, s72
	s_nop 0
	global_load_lds_dwordx4 v68, s[98:99]
	s_mov_b32 m0, s78
	s_nop 0
	global_load_lds_dwordx4 v70, s[98:99]
	s_mov_b32 m0, s79
	s_nop 0
	global_load_lds_dwordx4 v64, s[100:101]
	s_mov_b32 m0, s80
	s_nop 0
	global_load_lds_dwordx4 v66, s[100:101]
	s_mov_b32 m0, s81
	s_nop 0
	global_load_lds_dwordx4 v68, s[100:101]
	ds_read_b128 v[118:121], v111 offset:49152
	s_mov_b32 m0, s73
	s_nop 0
	global_load_lds_dwordx4 v70, s[100:101]
	s_add_u32 s98, s98, 0x80
	s_addc_u32 s99, s99, 0
	s_add_u32 s100, s100, 0x80
	s_addc_u32 s101, s101, 0
	ds_read_b128 v[122:125], v110 offset:32768
	ds_read_b128 v[126:129], v110 offset:36864
	s_waitcnt lgkmcnt(0)
	v_mfma_f32_32x32x16_bf16 v[32:47], v[118:121], v[122:125], v[32:47]
	s_mov_b32 m0, s11
	v_mfma_f32_32x32x16_bf16 v[0:15], v[118:121], v[126:129], v[0:15]
	ds_read_b128 v[118:121], v111 offset:53248
	s_waitcnt lgkmcnt(0)
	v_mfma_f32_32x32x16_bf16 v[48:63], v[118:121], v[122:125], v[48:63]
	v_mfma_f32_32x32x16_bf16 v[16:31], v[118:121], v[126:129], v[16:31]
	ds_read_b128 v[118:121], v113 offset:49152
	ds_read_b128 v[122:125], v112 offset:32768
	ds_read_b128 v[126:129], v112 offset:36864
	s_waitcnt lgkmcnt(0)
	v_mfma_f32_32x32x16_bf16 v[32:47], v[118:121], v[122:125], v[32:47]
	v_mfma_f32_32x32x16_bf16 v[0:15], v[118:121], v[126:129], v[0:15]
	ds_read_b128 v[118:121], v113 offset:53248
	s_waitcnt lgkmcnt(0)
	v_mfma_f32_32x32x16_bf16 v[48:63], v[118:121], v[122:125], v[48:63]
	v_mfma_f32_32x32x16_bf16 v[16:31], v[118:121], v[126:129], v[16:31]
	ds_read_b128 v[118:121], v115 offset:49152
	ds_read_b128 v[122:125], v114 offset:32768
	ds_read_b128 v[126:129], v114 offset:36864
	s_waitcnt lgkmcnt(0)
	v_mfma_f32_32x32x16_bf16 v[32:47], v[118:121], v[122:125], v[32:47]
	v_mfma_f32_32x32x16_bf16 v[0:15], v[118:121], v[126:129], v[0:15]
	ds_read_b128 v[118:121], v115 offset:53248
	s_waitcnt lgkmcnt(0)
	v_mfma_f32_32x32x16_bf16 v[48:63], v[118:121], v[122:125], v[48:63]
	v_mfma_f32_32x32x16_bf16 v[16:31], v[118:121], v[126:129], v[16:31]
	ds_read_b128 v[118:121], v117 offset:49152
	ds_read_b128 v[122:125], v116 offset:32768
	ds_read_b128 v[126:129], v116 offset:36864
	s_waitcnt lgkmcnt(0)
	v_mfma_f32_32x32x16_bf16 v[32:47], v[118:121], v[122:125], v[32:47]
	v_mfma_f32_32x32x16_bf16 v[0:15], v[118:121], v[126:129], v[0:15]
	ds_read_b128 v[118:121], v117 offset:53248
	s_waitcnt vmcnt(0)
	s_waitcnt vmcnt(0) lgkmcnt(0)
	s_barrier
	v_mfma_f32_32x32x16_bf16 v[48:63], v[118:121], v[122:125], v[48:63]
	v_mfma_f32_32x32x16_bf16 v[16:31], v[118:121], v[126:129], v[16:31]
	global_load_lds_dwordx4 v64, s[98:99]
	s_mov_b32 m0, s15
	s_nop 0
	global_load_lds_dwordx4 v66, s[98:99]
	s_mov_b32 m0, s28
	s_nop 0
	global_load_lds_dwordx4 v68, s[98:99]
	s_mov_b32 m0, s29
	s_nop 0
	global_load_lds_dwordx4 v70, s[98:99]
	s_mov_b32 m0, s30
	s_nop 0
	global_load_lds_dwordx4 v64, s[100:101]
	s_mov_b32 m0, s31
	s_nop 0
	global_load_lds_dwordx4 v66, s[100:101]
	ds_read_b128 v[118:121], v111 offset:16384
	s_mov_b32 m0, s34
	s_nop 0
	global_load_lds_dwordx4 v68, s[100:101]
	s_mov_b32 m0, s35
	ds_read_b128 v[122:125], v110
	global_load_lds_dwordx4 v70, s[100:101]
	s_add_u32 s98, s98, 0x80
	s_addc_u32 s99, s99, 0
	s_add_u32 s100, s100, 0x80
	s_addc_u32 s101, s101, 0
	ds_read_b128 v[126:129], v110 offset:4096
	s_waitcnt lgkmcnt(0)
	v_mfma_f32_32x32x16_bf16 v[32:47], v[118:121], v[122:125], v[32:47]
	s_mov_b32 m0, s70
	v_mfma_f32_32x32x16_bf16 v[0:15], v[118:121], v[126:129], v[0:15]
	ds_read_b128 v[118:121], v111 offset:20480
	s_waitcnt lgkmcnt(0)
	v_mfma_f32_32x32x16_bf16 v[48:63], v[118:121], v[122:125], v[48:63]
	v_mfma_f32_32x32x16_bf16 v[16:31], v[118:121], v[126:129], v[16:31]
	ds_read_b128 v[118:121], v113 offset:16384
	ds_read_b128 v[122:125], v112
	ds_read_b128 v[126:129], v112 offset:4096
	s_waitcnt lgkmcnt(0)
	v_mfma_f32_32x32x16_bf16 v[32:47], v[118:121], v[122:125], v[32:47]
	v_mfma_f32_32x32x16_bf16 v[0:15], v[118:121], v[126:129], v[0:15]
	ds_read_b128 v[118:121], v113 offset:20480
	s_waitcnt lgkmcnt(0)
	v_mfma_f32_32x32x16_bf16 v[48:63], v[118:121], v[122:125], v[48:63]
	v_mfma_f32_32x32x16_bf16 v[16:31], v[118:121], v[126:129], v[16:31]
	ds_read_b128 v[118:121], v115 offset:16384
	ds_read_b128 v[122:125], v114
	ds_read_b128 v[126:129], v114 offset:4096
	s_waitcnt lgkmcnt(0)
	v_mfma_f32_32x32x16_bf16 v[32:47], v[118:121], v[122:125], v[32:47]
	v_mfma_f32_32x32x16_bf16 v[0:15], v[118:121], v[126:129], v[0:15]
	ds_read_b128 v[118:121], v115 offset:20480
	s_waitcnt lgkmcnt(0)
	v_mfma_f32_32x32x16_bf16 v[48:63], v[118:121], v[122:125], v[48:63]
	v_mfma_f32_32x32x16_bf16 v[16:31], v[118:121], v[126:129], v[16:31]
	ds_read_b128 v[118:121], v117 offset:16384
	ds_read_b128 v[122:125], v116
	ds_read_b128 v[126:129], v116 offset:4096
	s_waitcnt lgkmcnt(0)
	v_mfma_f32_32x32x16_bf16 v[32:47], v[118:121], v[122:125], v[32:47]
	v_mfma_f32_32x32x16_bf16 v[0:15], v[118:121], v[126:129], v[0:15]
	ds_read_b128 v[118:121], v117 offset:20480
	s_waitcnt vmcnt(0)
	s_waitcnt vmcnt(0) lgkmcnt(0)
	s_barrier
	v_mfma_f32_32x32x16_bf16 v[48:63], v[118:121], v[122:125], v[48:63]
	v_mfma_f32_32x32x16_bf16 v[16:31], v[118:121], v[126:129], v[16:31]
	global_load_lds_dwordx4 v64, s[98:99]
	s_mov_b32 m0, s71
	s_nop 0
	global_load_lds_dwordx4 v66, s[98:99]
	s_mov_b32 m0, s72
	s_nop 0
	global_load_lds_dwordx4 v68, s[98:99]
	s_mov_b32 m0, s78
	s_nop 0
	global_load_lds_dwordx4 v70, s[98:99]
	s_mov_b32 m0, s79
	s_nop 0
	global_load_lds_dwordx4 v64, s[100:101]
	s_mov_b32 m0, s80
	s_nop 0
	global_load_lds_dwordx4 v66, s[100:101]
	s_mov_b32 m0, s81
	s_nop 0
	global_load_lds_dwordx4 v68, s[100:101]
	ds_read_b128 v[118:121], v111 offset:49152
	s_mov_b32 m0, s73
	s_nop 0
	global_load_lds_dwordx4 v70, s[100:101]
	s_add_u32 s98, s98, 0x80
	s_addc_u32 s99, s99, 0
	s_add_u32 s100, s100, 0x80
	s_addc_u32 s101, s101, 0
	ds_read_b128 v[122:125], v110 offset:32768
	ds_read_b128 v[126:129], v110 offset:36864
	s_waitcnt lgkmcnt(0)
	v_mfma_f32_32x32x16_bf16 v[32:47], v[118:121], v[122:125], v[32:47]
	s_mov_b32 m0, s11
	v_mfma_f32_32x32x16_bf16 v[0:15], v[118:121], v[126:129], v[0:15]
	ds_read_b128 v[118:121], v111 offset:53248
	s_waitcnt lgkmcnt(0)
	v_mfma_f32_32x32x16_bf16 v[48:63], v[118:121], v[122:125], v[48:63]
	v_mfma_f32_32x32x16_bf16 v[16:31], v[118:121], v[126:129], v[16:31]
	ds_read_b128 v[118:121], v113 offset:49152
	ds_read_b128 v[122:125], v112 offset:32768
	ds_read_b128 v[126:129], v112 offset:36864
	s_waitcnt lgkmcnt(0)
	v_mfma_f32_32x32x16_bf16 v[32:47], v[118:121], v[122:125], v[32:47]
	v_mfma_f32_32x32x16_bf16 v[0:15], v[118:121], v[126:129], v[0:15]
	ds_read_b128 v[118:121], v113 offset:53248
	s_waitcnt lgkmcnt(0)
	v_mfma_f32_32x32x16_bf16 v[48:63], v[118:121], v[122:125], v[48:63]
	v_mfma_f32_32x32x16_bf16 v[16:31], v[118:121], v[126:129], v[16:31]
	ds_read_b128 v[118:121], v115 offset:49152
	ds_read_b128 v[122:125], v114 offset:32768
	ds_read_b128 v[126:129], v114 offset:36864
	s_waitcnt lgkmcnt(0)
	v_mfma_f32_32x32x16_bf16 v[32:47], v[118:121], v[122:125], v[32:47]
	v_mfma_f32_32x32x16_bf16 v[0:15], v[118:121], v[126:129], v[0:15]
	ds_read_b128 v[118:121], v115 offset:53248
	s_waitcnt lgkmcnt(0)
	v_mfma_f32_32x32x16_bf16 v[48:63], v[118:121], v[122:125], v[48:63]
	v_mfma_f32_32x32x16_bf16 v[16:31], v[118:121], v[126:129], v[16:31]
	ds_read_b128 v[118:121], v117 offset:49152
	ds_read_b128 v[122:125], v116 offset:32768
	ds_read_b128 v[126:129], v116 offset:36864
	s_waitcnt lgkmcnt(0)
	v_mfma_f32_32x32x16_bf16 v[32:47], v[118:121], v[122:125], v[32:47]
	v_mfma_f32_32x32x16_bf16 v[0:15], v[118:121], v[126:129], v[0:15]
	ds_read_b128 v[118:121], v117 offset:53248
	s_waitcnt vmcnt(0)
	s_waitcnt vmcnt(0) lgkmcnt(0)
	s_barrier
	v_mfma_f32_32x32x16_bf16 v[48:63], v[118:121], v[122:125], v[48:63]
	v_mfma_f32_32x32x16_bf16 v[16:31], v[118:121], v[126:129], v[16:31]
	global_load_lds_dwordx4 v64, s[98:99]
	s_mov_b32 m0, s15
	s_nop 0
	global_load_lds_dwordx4 v66, s[98:99]
	s_mov_b32 m0, s28
	s_nop 0
	global_load_lds_dwordx4 v68, s[98:99]
	s_mov_b32 m0, s29
	s_nop 0
	global_load_lds_dwordx4 v70, s[98:99]
	s_mov_b32 m0, s30
	s_nop 0
	global_load_lds_dwordx4 v64, s[100:101]
	s_mov_b32 m0, s31
	s_nop 0
	global_load_lds_dwordx4 v66, s[100:101]
	ds_read_b128 v[118:121], v111 offset:16384
	s_mov_b32 m0, s34
	s_nop 0
	global_load_lds_dwordx4 v68, s[100:101]
	s_mov_b32 m0, s35
	ds_read_b128 v[122:125], v110
	global_load_lds_dwordx4 v70, s[100:101]
	s_add_u32 s98, s98, 0x80
	s_addc_u32 s99, s99, 0
	s_add_u32 s100, s100, 0x80
	s_addc_u32 s101, s101, 0
	ds_read_b128 v[126:129], v110 offset:4096
	s_waitcnt lgkmcnt(0)
	v_mfma_f32_32x32x16_bf16 v[32:47], v[118:121], v[122:125], v[32:47]
	s_mov_b32 m0, s70
	v_mfma_f32_32x32x16_bf16 v[0:15], v[118:121], v[126:129], v[0:15]
	ds_read_b128 v[118:121], v111 offset:20480
	s_waitcnt lgkmcnt(0)
	v_mfma_f32_32x32x16_bf16 v[48:63], v[118:121], v[122:125], v[48:63]
	v_mfma_f32_32x32x16_bf16 v[16:31], v[118:121], v[126:129], v[16:31]
	ds_read_b128 v[118:121], v113 offset:16384
	ds_read_b128 v[122:125], v112
	ds_read_b128 v[126:129], v112 offset:4096
	s_waitcnt lgkmcnt(0)
	v_mfma_f32_32x32x16_bf16 v[32:47], v[118:121], v[122:125], v[32:47]
	v_mfma_f32_32x32x16_bf16 v[0:15], v[118:121], v[126:129], v[0:15]
	ds_read_b128 v[118:121], v113 offset:20480
	s_waitcnt lgkmcnt(0)
	v_mfma_f32_32x32x16_bf16 v[48:63], v[118:121], v[122:125], v[48:63]
	v_mfma_f32_32x32x16_bf16 v[16:31], v[118:121], v[126:129], v[16:31]
	ds_read_b128 v[118:121], v115 offset:16384
	ds_read_b128 v[122:125], v114
	ds_read_b128 v[126:129], v114 offset:4096
	s_waitcnt lgkmcnt(0)
	v_mfma_f32_32x32x16_bf16 v[32:47], v[118:121], v[122:125], v[32:47]
	v_mfma_f32_32x32x16_bf16 v[0:15], v[118:121], v[126:129], v[0:15]
	ds_read_b128 v[118:121], v115 offset:20480
	s_waitcnt lgkmcnt(0)
	v_mfma_f32_32x32x16_bf16 v[48:63], v[118:121], v[122:125], v[48:63]
	v_mfma_f32_32x32x16_bf16 v[16:31], v[118:121], v[126:129], v[16:31]
	ds_read_b128 v[118:121], v117 offset:16384
	ds_read_b128 v[122:125], v116
	ds_read_b128 v[126:129], v116 offset:4096
	s_waitcnt lgkmcnt(0)
	v_mfma_f32_32x32x16_bf16 v[32:47], v[118:121], v[122:125], v[32:47]
	v_mfma_f32_32x32x16_bf16 v[0:15], v[118:121], v[126:129], v[0:15]
	ds_read_b128 v[118:121], v117 offset:20480
	s_waitcnt vmcnt(0)
	s_waitcnt vmcnt(0) lgkmcnt(0)
	s_barrier
	v_mfma_f32_32x32x16_bf16 v[48:63], v[118:121], v[122:125], v[48:63]
	v_mfma_f32_32x32x16_bf16 v[16:31], v[118:121], v[126:129], v[16:31]
	global_load_lds_dwordx4 v64, s[98:99]
	s_mov_b32 m0, s71
	s_nop 0
	global_load_lds_dwordx4 v66, s[98:99]
	s_mov_b32 m0, s72
	s_nop 0
	global_load_lds_dwordx4 v68, s[98:99]
	s_mov_b32 m0, s78
	s_nop 0
	global_load_lds_dwordx4 v70, s[98:99]
	s_mov_b32 m0, s79
	s_nop 0
	global_load_lds_dwordx4 v64, s[100:101]
	s_mov_b32 m0, s80
	s_nop 0
	global_load_lds_dwordx4 v66, s[100:101]
	s_mov_b32 m0, s81
	s_nop 0
	global_load_lds_dwordx4 v68, s[100:101]
	ds_read_b128 v[118:121], v111 offset:49152
	s_mov_b32 m0, s73
	s_nop 0
	global_load_lds_dwordx4 v70, s[100:101]
	s_add_u32 s98, s98, 0x80
	s_addc_u32 s99, s99, 0
	s_add_u32 s100, s100, 0x80
	s_addc_u32 s101, s101, 0
	ds_read_b128 v[122:125], v110 offset:32768
	ds_read_b128 v[126:129], v110 offset:36864
	s_waitcnt lgkmcnt(0)
	v_mfma_f32_32x32x16_bf16 v[32:47], v[118:121], v[122:125], v[32:47]
	s_mov_b32 m0, s11
	v_mfma_f32_32x32x16_bf16 v[0:15], v[118:121], v[126:129], v[0:15]
	ds_read_b128 v[118:121], v111 offset:53248
	s_waitcnt lgkmcnt(0)
	v_mfma_f32_32x32x16_bf16 v[48:63], v[118:121], v[122:125], v[48:63]
	v_mfma_f32_32x32x16_bf16 v[16:31], v[118:121], v[126:129], v[16:31]
	ds_read_b128 v[118:121], v113 offset:49152
	ds_read_b128 v[122:125], v112 offset:32768
	ds_read_b128 v[126:129], v112 offset:36864
	s_waitcnt lgkmcnt(0)
	v_mfma_f32_32x32x16_bf16 v[32:47], v[118:121], v[122:125], v[32:47]
	v_mfma_f32_32x32x16_bf16 v[0:15], v[118:121], v[126:129], v[0:15]
	ds_read_b128 v[118:121], v113 offset:53248
	s_waitcnt lgkmcnt(0)
	v_mfma_f32_32x32x16_bf16 v[48:63], v[118:121], v[122:125], v[48:63]
	v_mfma_f32_32x32x16_bf16 v[16:31], v[118:121], v[126:129], v[16:31]
	ds_read_b128 v[118:121], v115 offset:49152
	ds_read_b128 v[122:125], v114 offset:32768
	ds_read_b128 v[126:129], v114 offset:36864
	s_waitcnt lgkmcnt(0)
	v_mfma_f32_32x32x16_bf16 v[32:47], v[118:121], v[122:125], v[32:47]
	v_mfma_f32_32x32x16_bf16 v[0:15], v[118:121], v[126:129], v[0:15]
	ds_read_b128 v[118:121], v115 offset:53248
	s_waitcnt lgkmcnt(0)
	v_mfma_f32_32x32x16_bf16 v[48:63], v[118:121], v[122:125], v[48:63]
	v_mfma_f32_32x32x16_bf16 v[16:31], v[118:121], v[126:129], v[16:31]
	ds_read_b128 v[118:121], v117 offset:49152
	ds_read_b128 v[122:125], v116 offset:32768
	ds_read_b128 v[126:129], v116 offset:36864
	s_waitcnt lgkmcnt(0)
	v_mfma_f32_32x32x16_bf16 v[32:47], v[118:121], v[122:125], v[32:47]
	v_mfma_f32_32x32x16_bf16 v[0:15], v[118:121], v[126:129], v[0:15]
	ds_read_b128 v[118:121], v117 offset:53248
	s_waitcnt vmcnt(0)
	s_waitcnt vmcnt(0) lgkmcnt(0)
	s_barrier
	v_mfma_f32_32x32x16_bf16 v[48:63], v[118:121], v[122:125], v[48:63]
	v_mfma_f32_32x32x16_bf16 v[16:31], v[118:121], v[126:129], v[16:31]
	global_load_lds_dwordx4 v64, s[98:99]
	s_mov_b32 m0, s15
	s_nop 0
	global_load_lds_dwordx4 v66, s[98:99]
	s_mov_b32 m0, s28
	s_nop 0
	global_load_lds_dwordx4 v68, s[98:99]
	s_mov_b32 m0, s29
	s_nop 0
	global_load_lds_dwordx4 v70, s[98:99]
	s_mov_b32 m0, s30
	s_nop 0
	global_load_lds_dwordx4 v64, s[100:101]
	s_mov_b32 m0, s31
	s_nop 0
	global_load_lds_dwordx4 v66, s[100:101]
	ds_read_b128 v[118:121], v111 offset:16384
	s_mov_b32 m0, s34
	s_nop 0
	global_load_lds_dwordx4 v68, s[100:101]
	s_mov_b32 m0, s35
	ds_read_b128 v[122:125], v110
	global_load_lds_dwordx4 v70, s[100:101]
	s_add_u32 s98, s98, 0x80
	s_addc_u32 s99, s99, 0
	s_add_u32 s100, s100, 0x80
	s_addc_u32 s101, s101, 0
	ds_read_b128 v[126:129], v110 offset:4096
	s_waitcnt lgkmcnt(0)
	v_mfma_f32_32x32x16_bf16 v[32:47], v[118:121], v[122:125], v[32:47]
	s_mov_b32 m0, s70
	v_readfirstlane_b32 s70, v102
	v_mfma_f32_32x32x16_bf16 v[0:15], v[118:121], v[126:129], v[0:15]
	ds_read_b128 v[118:121], v111 offset:20480
	s_waitcnt lgkmcnt(0)
	v_mfma_f32_32x32x16_bf16 v[48:63], v[118:121], v[122:125], v[48:63]
	v_mfma_f32_32x32x16_bf16 v[16:31], v[118:121], v[126:129], v[16:31]
	ds_read_b128 v[118:121], v113 offset:16384
	ds_read_b128 v[122:125], v112
	ds_read_b128 v[126:129], v112 offset:4096
	s_waitcnt lgkmcnt(0)
	v_mfma_f32_32x32x16_bf16 v[32:47], v[118:121], v[122:125], v[32:47]
	v_mfma_f32_32x32x16_bf16 v[0:15], v[118:121], v[126:129], v[0:15]
	ds_read_b128 v[118:121], v113 offset:20480
	s_waitcnt lgkmcnt(0)
	v_mfma_f32_32x32x16_bf16 v[48:63], v[118:121], v[122:125], v[48:63]
	v_mfma_f32_32x32x16_bf16 v[16:31], v[118:121], v[126:129], v[16:31]
	ds_read_b128 v[118:121], v115 offset:16384
	ds_read_b128 v[122:125], v114
	ds_read_b128 v[126:129], v114 offset:4096
	s_waitcnt lgkmcnt(0)
	v_mfma_f32_32x32x16_bf16 v[32:47], v[118:121], v[122:125], v[32:47]
	v_mfma_f32_32x32x16_bf16 v[0:15], v[118:121], v[126:129], v[0:15]
	ds_read_b128 v[118:121], v115 offset:20480
	s_waitcnt lgkmcnt(0)
	v_mfma_f32_32x32x16_bf16 v[48:63], v[118:121], v[122:125], v[48:63]
	v_mfma_f32_32x32x16_bf16 v[16:31], v[118:121], v[126:129], v[16:31]
	ds_read_b128 v[118:121], v117 offset:16384
	ds_read_b128 v[122:125], v116
	ds_read_b128 v[126:129], v116 offset:4096
	s_waitcnt lgkmcnt(0)
	v_mfma_f32_32x32x16_bf16 v[32:47], v[118:121], v[122:125], v[32:47]
	v_mfma_f32_32x32x16_bf16 v[0:15], v[118:121], v[126:129], v[0:15]
	ds_read_b128 v[118:121], v117 offset:20480
	s_waitcnt vmcnt(0)
	s_waitcnt vmcnt(0) lgkmcnt(0)
	s_barrier
	v_mfma_f32_32x32x16_bf16 v[48:63], v[118:121], v[122:125], v[48:63]
	v_mfma_f32_32x32x16_bf16 v[16:31], v[118:121], v[126:129], v[16:31]
	global_load_lds_dwordx4 v64, s[98:99]
	s_mov_b32 m0, s71
	v_readfirstlane_b32 s71, v103
	global_load_lds_dwordx4 v66, s[98:99]
	s_mov_b32 m0, s72
	v_readfirstlane_b32 s72, v104
	global_load_lds_dwordx4 v68, s[98:99]
	s_mov_b32 m0, s78
	v_readfirstlane_b32 s78, v106
	global_load_lds_dwordx4 v70, s[98:99]
	s_mov_b32 m0, s79
	v_readfirstlane_b32 s79, v107
	global_load_lds_dwordx4 v64, s[100:101]
	s_mov_b32 m0, s80
	v_readfirstlane_b32 s80, v108
	global_load_lds_dwordx4 v66, s[100:101]
	s_mov_b32 m0, s81
	v_readfirstlane_b32 s81, v109
	global_load_lds_dwordx4 v68, s[100:101]
	ds_read_b128 v[118:121], v111 offset:49152
	s_mov_b32 m0, s73
	v_readfirstlane_b32 s73, v105
	global_load_lds_dwordx4 v70, s[100:101]
	s_add_u32 s98, s98, 0x80
	s_addc_u32 s99, s99, 0
	s_add_u32 s100, s100, 0x80
	s_addc_u32 s101, s101, 0
	ds_read_b128 v[122:125], v110 offset:32768
	ds_read_b128 v[126:129], v110 offset:36864
	s_waitcnt lgkmcnt(0)
	v_mfma_f32_32x32x16_bf16 v[32:47], v[118:121], v[122:125], v[32:47]
	s_mov_b32 m0, s11
	v_readfirstlane_b32 s11, v92
	v_mfma_f32_32x32x16_bf16 v[0:15], v[118:121], v[126:129], v[0:15]
	ds_read_b128 v[118:121], v111 offset:53248
	s_waitcnt lgkmcnt(0)
	v_mfma_f32_32x32x16_bf16 v[48:63], v[118:121], v[122:125], v[48:63]
	v_mfma_f32_32x32x16_bf16 v[16:31], v[118:121], v[126:129], v[16:31]
	ds_read_b128 v[118:121], v113 offset:49152
	ds_read_b128 v[122:125], v112 offset:32768
	ds_read_b128 v[126:129], v112 offset:36864
	s_waitcnt lgkmcnt(0)
	v_mfma_f32_32x32x16_bf16 v[32:47], v[118:121], v[122:125], v[32:47]
	v_mfma_f32_32x32x16_bf16 v[0:15], v[118:121], v[126:129], v[0:15]
	ds_read_b128 v[118:121], v113 offset:53248
	s_waitcnt lgkmcnt(0)
	v_mfma_f32_32x32x16_bf16 v[48:63], v[118:121], v[122:125], v[48:63]
	v_mfma_f32_32x32x16_bf16 v[16:31], v[118:121], v[126:129], v[16:31]
	ds_read_b128 v[118:121], v115 offset:49152
	ds_read_b128 v[122:125], v114 offset:32768
	ds_read_b128 v[126:129], v114 offset:36864
	s_waitcnt lgkmcnt(0)
	v_mfma_f32_32x32x16_bf16 v[32:47], v[118:121], v[122:125], v[32:47]
	v_mfma_f32_32x32x16_bf16 v[0:15], v[118:121], v[126:129], v[0:15]
	ds_read_b128 v[118:121], v115 offset:53248
	s_waitcnt lgkmcnt(0)
	v_mfma_f32_32x32x16_bf16 v[48:63], v[118:121], v[122:125], v[48:63]
	v_mfma_f32_32x32x16_bf16 v[16:31], v[118:121], v[126:129], v[16:31]
	ds_read_b128 v[118:121], v117 offset:49152
	ds_read_b128 v[122:125], v116 offset:32768
	ds_read_b128 v[126:129], v116 offset:36864
	s_waitcnt lgkmcnt(0)
	v_mfma_f32_32x32x16_bf16 v[32:47], v[118:121], v[122:125], v[32:47]
	v_mfma_f32_32x32x16_bf16 v[0:15], v[118:121], v[126:129], v[0:15]
	ds_read_b128 v[118:121], v117 offset:53248
	s_waitcnt vmcnt(0)
	s_waitcnt vmcnt(0) lgkmcnt(0)
	s_barrier
	v_mfma_f32_32x32x16_bf16 v[48:63], v[118:121], v[122:125], v[48:63]
	v_mfma_f32_32x32x16_bf16 v[16:31], v[118:121], v[126:129], v[16:31]
	global_load_lds_dwordx4 v64, s[98:99]
	s_mov_b32 m0, s15
	s_nop 0
	global_load_lds_dwordx4 v66, s[98:99]
	s_mov_b32 m0, s28
	v_readfirstlane_b32 s15, v95
	global_load_lds_dwordx4 v68, s[98:99]
	s_mov_b32 m0, s29
	v_readfirstlane_b32 s28, v96
	global_load_lds_dwordx4 v70, s[98:99]
	s_mov_b32 m0, s30
	v_readfirstlane_b32 s30, v97
	global_load_lds_dwordx4 v64, s[100:101]
	s_mov_b32 m0, s31
	v_readfirstlane_b32 s31, v98
	global_load_lds_dwordx4 v66, s[100:101]
	ds_read_b128 v[118:121], v111 offset:16384
	s_mov_b32 m0, s34
	v_readfirstlane_b32 s34, v99
	global_load_lds_dwordx4 v68, s[100:101]
	s_mov_b32 m0, s35
	ds_read_b128 v[122:125], v110
	global_load_lds_dwordx4 v70, s[100:101]
	s_add_u32 s98, s98, 0x80
	s_addc_u32 s99, s99, 0
	s_add_u32 s100, s100, 0x80
	s_addc_u32 s101, s101, 0
	ds_read_b128 v[126:129], v110 offset:4096
	s_waitcnt lgkmcnt(0)
	v_mfma_f32_32x32x16_bf16 v[32:47], v[118:121], v[122:125], v[32:47]
	s_mov_b32 m0, s11
	v_readfirstlane_b32 s35, v100
	v_readfirstlane_b32 s29, v101
	v_mfma_f32_32x32x16_bf16 v[0:15], v[118:121], v[126:129], v[0:15]
	ds_read_b128 v[118:121], v111 offset:20480
	s_waitcnt lgkmcnt(0)
	v_mfma_f32_32x32x16_bf16 v[48:63], v[118:121], v[122:125], v[48:63]
	v_mfma_f32_32x32x16_bf16 v[16:31], v[118:121], v[126:129], v[16:31]
	ds_read_b128 v[118:121], v113 offset:16384
	ds_read_b128 v[122:125], v112
	ds_read_b128 v[126:129], v112 offset:4096
	s_waitcnt lgkmcnt(0)
	v_mfma_f32_32x32x16_bf16 v[32:47], v[118:121], v[122:125], v[32:47]
	v_mfma_f32_32x32x16_bf16 v[0:15], v[118:121], v[126:129], v[0:15]
	ds_read_b128 v[118:121], v113 offset:20480
	s_waitcnt lgkmcnt(0)
	v_mfma_f32_32x32x16_bf16 v[48:63], v[118:121], v[122:125], v[48:63]
	v_mfma_f32_32x32x16_bf16 v[16:31], v[118:121], v[126:129], v[16:31]
	ds_read_b128 v[118:121], v115 offset:16384
	ds_read_b128 v[122:125], v114
	ds_read_b128 v[126:129], v114 offset:4096
	s_waitcnt lgkmcnt(0)
	v_mfma_f32_32x32x16_bf16 v[32:47], v[118:121], v[122:125], v[32:47]
	v_mfma_f32_32x32x16_bf16 v[0:15], v[118:121], v[126:129], v[0:15]
	ds_read_b128 v[118:121], v115 offset:20480
	s_waitcnt lgkmcnt(0)
	v_mfma_f32_32x32x16_bf16 v[48:63], v[118:121], v[122:125], v[48:63]
	v_mfma_f32_32x32x16_bf16 v[16:31], v[118:121], v[126:129], v[16:31]
	ds_read_b128 v[118:121], v117 offset:16384
	ds_read_b128 v[122:125], v116
	ds_read_b128 v[126:129], v116 offset:4096
	s_waitcnt lgkmcnt(0)
	v_mfma_f32_32x32x16_bf16 v[32:47], v[118:121], v[122:125], v[32:47]
	v_mfma_f32_32x32x16_bf16 v[0:15], v[118:121], v[126:129], v[0:15]
	ds_read_b128 v[118:121], v117 offset:20480
	s_waitcnt vmcnt(0)
	s_waitcnt vmcnt(0) lgkmcnt(0)
	s_barrier
	v_mfma_f32_32x32x16_bf16 v[48:63], v[118:121], v[122:125], v[48:63]
	v_mfma_f32_32x32x16_bf16 v[16:31], v[118:121], v[126:129], v[16:31]
	global_load_lds_dwordx4 v64, s[98:99]
	s_mov_b32 m0, s15
	s_nop 0
	global_load_lds_dwordx4 v66, s[98:99]
	s_mov_b32 m0, s28
	s_nop 0
	global_load_lds_dwordx4 v68, s[98:99]
	s_mov_b32 m0, s30
	s_nop 0
	global_load_lds_dwordx4 v70, s[98:99]
	s_mov_b32 m0, s31
	s_nop 0
	global_load_lds_dwordx4 v64, s[100:101]
	s_mov_b32 m0, s34
	s_nop 0
	global_load_lds_dwordx4 v66, s[100:101]
	s_mov_b32 m0, s35
	s_nop 0
	global_load_lds_dwordx4 v68, s[100:101]
	ds_read_b128 v[118:121], v111 offset:49152
	s_mov_b32 m0, s29
	s_nop 0
	global_load_lds_dwordx4 v70, s[100:101]
	s_add_u32 s98, s98, 0x80
	s_addc_u32 s99, s99, 0
	s_add_u32 s100, s100, 0x80
	s_addc_u32 s101, s101, 0
	ds_read_b128 v[122:125], v110 offset:32768
	ds_read_b128 v[126:129], v110 offset:36864
	s_waitcnt lgkmcnt(0)
	v_mfma_f32_32x32x16_bf16 v[32:47], v[118:121], v[122:125], v[32:47]
	s_mov_b32 m0, s70
	v_mfma_f32_32x32x16_bf16 v[0:15], v[118:121], v[126:129], v[0:15]
	ds_read_b128 v[118:121], v111 offset:53248
	s_waitcnt lgkmcnt(0)
	v_mfma_f32_32x32x16_bf16 v[48:63], v[118:121], v[122:125], v[48:63]
	v_mfma_f32_32x32x16_bf16 v[16:31], v[118:121], v[126:129], v[16:31]
	ds_read_b128 v[118:121], v113 offset:49152
	ds_read_b128 v[122:125], v112 offset:32768
	ds_read_b128 v[126:129], v112 offset:36864
	s_waitcnt lgkmcnt(0)
	v_mfma_f32_32x32x16_bf16 v[32:47], v[118:121], v[122:125], v[32:47]
	v_mfma_f32_32x32x16_bf16 v[0:15], v[118:121], v[126:129], v[0:15]
	ds_read_b128 v[118:121], v113 offset:53248
	s_waitcnt lgkmcnt(0)
	v_mfma_f32_32x32x16_bf16 v[48:63], v[118:121], v[122:125], v[48:63]
	v_mfma_f32_32x32x16_bf16 v[16:31], v[118:121], v[126:129], v[16:31]
	ds_read_b128 v[118:121], v115 offset:49152
	ds_read_b128 v[122:125], v114 offset:32768
	ds_read_b128 v[126:129], v114 offset:36864
	s_waitcnt lgkmcnt(0)
	v_mfma_f32_32x32x16_bf16 v[32:47], v[118:121], v[122:125], v[32:47]
	v_mfma_f32_32x32x16_bf16 v[0:15], v[118:121], v[126:129], v[0:15]
	ds_read_b128 v[118:121], v115 offset:53248
	s_waitcnt lgkmcnt(0)
	v_mfma_f32_32x32x16_bf16 v[48:63], v[118:121], v[122:125], v[48:63]
	v_mfma_f32_32x32x16_bf16 v[16:31], v[118:121], v[126:129], v[16:31]
	ds_read_b128 v[118:121], v117 offset:49152
	ds_read_b128 v[122:125], v116 offset:32768
	ds_read_b128 v[126:129], v116 offset:36864
	s_waitcnt lgkmcnt(0)
	v_mfma_f32_32x32x16_bf16 v[32:47], v[118:121], v[122:125], v[32:47]
	v_mfma_f32_32x32x16_bf16 v[0:15], v[118:121], v[126:129], v[0:15]
	ds_read_b128 v[118:121], v117 offset:53248
	s_waitcnt vmcnt(0)
	s_waitcnt vmcnt(0) lgkmcnt(0)
	s_barrier
	v_mfma_f32_32x32x16_bf16 v[48:63], v[118:121], v[122:125], v[48:63]
	v_mfma_f32_32x32x16_bf16 v[16:31], v[118:121], v[126:129], v[16:31]
	global_load_lds_dwordx4 v64, s[98:99]
	s_mov_b32 m0, s71
	s_nop 0
	global_load_lds_dwordx4 v66, s[98:99]
	s_mov_b32 m0, s72
	s_nop 0
	global_load_lds_dwordx4 v68, s[98:99]
	s_mov_b32 m0, s73
	s_nop 0
	global_load_lds_dwordx4 v70, s[98:99]
	s_mov_b32 m0, s78
	s_nop 0
	global_load_lds_dwordx4 v64, s[100:101]
	s_mov_b32 m0, s79
	s_nop 0
	global_load_lds_dwordx4 v66, s[100:101]
	ds_read_b128 v[118:121], v111 offset:16384
	s_mov_b32 m0, s80
	s_nop 0
	global_load_lds_dwordx4 v68, s[100:101]
	s_mov_b32 m0, s81
	ds_read_b128 v[122:125], v110
	global_load_lds_dwordx4 v70, s[100:101]
	s_add_u32 s98, s98, 0x80
	s_addc_u32 s99, s99, 0
	s_add_u32 s100, s100, 0x80
	s_addc_u32 s101, s101, 0
	ds_read_b128 v[126:129], v110 offset:4096
	s_waitcnt lgkmcnt(0)
	v_mfma_f32_32x32x16_bf16 v[32:47], v[118:121], v[122:125], v[32:47]
	s_mov_b32 m0, s11
	v_mfma_f32_32x32x16_bf16 v[0:15], v[118:121], v[126:129], v[0:15]
	ds_read_b128 v[118:121], v111 offset:20480
	s_waitcnt lgkmcnt(0)
	v_mfma_f32_32x32x16_bf16 v[48:63], v[118:121], v[122:125], v[48:63]
	v_mfma_f32_32x32x16_bf16 v[16:31], v[118:121], v[126:129], v[16:31]
	ds_read_b128 v[118:121], v113 offset:16384
	ds_read_b128 v[122:125], v112
	ds_read_b128 v[126:129], v112 offset:4096
	s_waitcnt lgkmcnt(0)
	v_mfma_f32_32x32x16_bf16 v[32:47], v[118:121], v[122:125], v[32:47]
	v_mfma_f32_32x32x16_bf16 v[0:15], v[118:121], v[126:129], v[0:15]
	ds_read_b128 v[118:121], v113 offset:20480
	s_waitcnt lgkmcnt(0)
	v_mfma_f32_32x32x16_bf16 v[48:63], v[118:121], v[122:125], v[48:63]
	v_mfma_f32_32x32x16_bf16 v[16:31], v[118:121], v[126:129], v[16:31]
	ds_read_b128 v[118:121], v115 offset:16384
	ds_read_b128 v[122:125], v114
	ds_read_b128 v[126:129], v114 offset:4096
	s_waitcnt lgkmcnt(0)
	v_mfma_f32_32x32x16_bf16 v[32:47], v[118:121], v[122:125], v[32:47]
	v_mfma_f32_32x32x16_bf16 v[0:15], v[118:121], v[126:129], v[0:15]
	ds_read_b128 v[118:121], v115 offset:20480
	s_waitcnt lgkmcnt(0)
	v_mfma_f32_32x32x16_bf16 v[48:63], v[118:121], v[122:125], v[48:63]
	v_mfma_f32_32x32x16_bf16 v[16:31], v[118:121], v[126:129], v[16:31]
	ds_read_b128 v[118:121], v117 offset:16384
	ds_read_b128 v[122:125], v116
	ds_read_b128 v[126:129], v116 offset:4096
	s_waitcnt lgkmcnt(0)
	v_mfma_f32_32x32x16_bf16 v[32:47], v[118:121], v[122:125], v[32:47]
	v_mfma_f32_32x32x16_bf16 v[0:15], v[118:121], v[126:129], v[0:15]
	ds_read_b128 v[118:121], v117 offset:20480
	s_waitcnt vmcnt(0)
	s_waitcnt vmcnt(0) lgkmcnt(0)
	s_barrier
	v_mfma_f32_32x32x16_bf16 v[48:63], v[118:121], v[122:125], v[48:63]
	v_mfma_f32_32x32x16_bf16 v[16:31], v[118:121], v[126:129], v[16:31]
	global_load_lds_dwordx4 v64, s[98:99]
	s_mov_b32 m0, s15
	s_nop 0
	global_load_lds_dwordx4 v66, s[98:99]
	s_mov_b32 m0, s28
	s_nop 0
	global_load_lds_dwordx4 v68, s[98:99]
	s_mov_b32 m0, s30
	s_nop 0
	global_load_lds_dwordx4 v70, s[98:99]
	s_mov_b32 m0, s31
	s_nop 0
	global_load_lds_dwordx4 v64, s[100:101]
	s_mov_b32 m0, s34
	s_nop 0
	global_load_lds_dwordx4 v66, s[100:101]
	s_mov_b32 m0, s35
	s_nop 0
	global_load_lds_dwordx4 v68, s[100:101]
	ds_read_b128 v[118:121], v111 offset:49152
	s_mov_b32 m0, s29
	s_nop 0
	global_load_lds_dwordx4 v70, s[100:101]
	s_add_u32 s98, s98, 0x80
	s_addc_u32 s99, s99, 0
	s_add_u32 s100, s100, 0x80
	s_addc_u32 s101, s101, 0
	ds_read_b128 v[122:125], v110 offset:32768
	ds_read_b128 v[126:129], v110 offset:36864
	s_waitcnt lgkmcnt(0)
	v_mfma_f32_32x32x16_bf16 v[32:47], v[118:121], v[122:125], v[32:47]
	s_mov_b32 m0, s70
	v_mfma_f32_32x32x16_bf16 v[0:15], v[118:121], v[126:129], v[0:15]
	ds_read_b128 v[118:121], v111 offset:53248
	s_waitcnt lgkmcnt(0)
	v_mfma_f32_32x32x16_bf16 v[48:63], v[118:121], v[122:125], v[48:63]
	v_mfma_f32_32x32x16_bf16 v[16:31], v[118:121], v[126:129], v[16:31]
	ds_read_b128 v[118:121], v113 offset:49152
	ds_read_b128 v[122:125], v112 offset:32768
	ds_read_b128 v[126:129], v112 offset:36864
	s_waitcnt lgkmcnt(0)
	v_mfma_f32_32x32x16_bf16 v[32:47], v[118:121], v[122:125], v[32:47]
	v_mfma_f32_32x32x16_bf16 v[0:15], v[118:121], v[126:129], v[0:15]
	ds_read_b128 v[118:121], v113 offset:53248
	s_waitcnt lgkmcnt(0)
	v_mfma_f32_32x32x16_bf16 v[48:63], v[118:121], v[122:125], v[48:63]
	v_mfma_f32_32x32x16_bf16 v[16:31], v[118:121], v[126:129], v[16:31]
	ds_read_b128 v[118:121], v115 offset:49152
	ds_read_b128 v[122:125], v114 offset:32768
	ds_read_b128 v[126:129], v114 offset:36864
	s_waitcnt lgkmcnt(0)
	v_mfma_f32_32x32x16_bf16 v[32:47], v[118:121], v[122:125], v[32:47]
	v_mfma_f32_32x32x16_bf16 v[0:15], v[118:121], v[126:129], v[0:15]
	ds_read_b128 v[118:121], v115 offset:53248
	s_waitcnt lgkmcnt(0)
	v_mfma_f32_32x32x16_bf16 v[48:63], v[118:121], v[122:125], v[48:63]
	v_mfma_f32_32x32x16_bf16 v[16:31], v[118:121], v[126:129], v[16:31]
	ds_read_b128 v[118:121], v117 offset:49152
	ds_read_b128 v[122:125], v116 offset:32768
	ds_read_b128 v[126:129], v116 offset:36864
	s_waitcnt lgkmcnt(0)
	v_mfma_f32_32x32x16_bf16 v[32:47], v[118:121], v[122:125], v[32:47]
	v_mfma_f32_32x32x16_bf16 v[0:15], v[118:121], v[126:129], v[0:15]
	ds_read_b128 v[118:121], v117 offset:53248
	s_waitcnt vmcnt(0)
	s_waitcnt vmcnt(0) lgkmcnt(0)
	s_barrier
	v_mfma_f32_32x32x16_bf16 v[48:63], v[118:121], v[122:125], v[48:63]
	v_mfma_f32_32x32x16_bf16 v[16:31], v[118:121], v[126:129], v[16:31]
	global_load_lds_dwordx4 v64, s[98:99]
	s_mov_b32 m0, s71
	s_nop 0
	global_load_lds_dwordx4 v66, s[98:99]
	s_mov_b32 m0, s72
	s_nop 0
	global_load_lds_dwordx4 v68, s[98:99]
	s_mov_b32 m0, s73
	s_nop 0
	global_load_lds_dwordx4 v70, s[98:99]
	s_mov_b32 m0, s78
	s_nop 0
	global_load_lds_dwordx4 v64, s[100:101]
	s_mov_b32 m0, s79
	s_nop 0
	global_load_lds_dwordx4 v66, s[100:101]
	ds_read_b128 v[118:121], v111 offset:16384
	s_mov_b32 m0, s80
	s_nop 0
	global_load_lds_dwordx4 v68, s[100:101]
	s_mov_b32 m0, s81
	ds_read_b128 v[122:125], v110
	global_load_lds_dwordx4 v70, s[100:101]
	s_add_u32 s98, s98, 0x80
	s_addc_u32 s99, s99, 0
	s_add_u32 s100, s100, 0x80
	s_addc_u32 s101, s101, 0
	ds_read_b128 v[126:129], v110 offset:4096
	s_waitcnt lgkmcnt(0)
	v_mfma_f32_32x32x16_bf16 v[32:47], v[118:121], v[122:125], v[32:47]
	s_mov_b32 m0, s11
	v_mfma_f32_32x32x16_bf16 v[0:15], v[118:121], v[126:129], v[0:15]
	ds_read_b128 v[118:121], v111 offset:20480
	s_waitcnt lgkmcnt(0)
	v_mfma_f32_32x32x16_bf16 v[48:63], v[118:121], v[122:125], v[48:63]
	v_mfma_f32_32x32x16_bf16 v[16:31], v[118:121], v[126:129], v[16:31]
	ds_read_b128 v[118:121], v113 offset:16384
	ds_read_b128 v[122:125], v112
	ds_read_b128 v[126:129], v112 offset:4096
	s_waitcnt lgkmcnt(0)
	v_mfma_f32_32x32x16_bf16 v[32:47], v[118:121], v[122:125], v[32:47]
	v_mfma_f32_32x32x16_bf16 v[0:15], v[118:121], v[126:129], v[0:15]
	ds_read_b128 v[118:121], v113 offset:20480
	s_waitcnt lgkmcnt(0)
	v_mfma_f32_32x32x16_bf16 v[48:63], v[118:121], v[122:125], v[48:63]
	v_mfma_f32_32x32x16_bf16 v[16:31], v[118:121], v[126:129], v[16:31]
	ds_read_b128 v[118:121], v115 offset:16384
	ds_read_b128 v[122:125], v114
	ds_read_b128 v[126:129], v114 offset:4096
	s_waitcnt lgkmcnt(0)
	v_mfma_f32_32x32x16_bf16 v[32:47], v[118:121], v[122:125], v[32:47]
	v_mfma_f32_32x32x16_bf16 v[0:15], v[118:121], v[126:129], v[0:15]
	ds_read_b128 v[118:121], v115 offset:20480
	s_waitcnt lgkmcnt(0)
	v_mfma_f32_32x32x16_bf16 v[48:63], v[118:121], v[122:125], v[48:63]
	v_mfma_f32_32x32x16_bf16 v[16:31], v[118:121], v[126:129], v[16:31]
	ds_read_b128 v[118:121], v117 offset:16384
	ds_read_b128 v[122:125], v116
	ds_read_b128 v[126:129], v116 offset:4096
	s_waitcnt lgkmcnt(0)
	v_mfma_f32_32x32x16_bf16 v[32:47], v[118:121], v[122:125], v[32:47]
	v_mfma_f32_32x32x16_bf16 v[0:15], v[118:121], v[126:129], v[0:15]
	ds_read_b128 v[118:121], v117 offset:20480
	s_waitcnt vmcnt(0)
	s_waitcnt vmcnt(0) lgkmcnt(0)
	s_barrier
	v_mfma_f32_32x32x16_bf16 v[48:63], v[118:121], v[122:125], v[48:63]
	v_mfma_f32_32x32x16_bf16 v[16:31], v[118:121], v[126:129], v[16:31]
	global_load_lds_dwordx4 v64, s[98:99]
	s_mov_b32 m0, s15
	s_nop 0
	global_load_lds_dwordx4 v66, s[98:99]
	s_mov_b32 m0, s28
	s_nop 0
	global_load_lds_dwordx4 v68, s[98:99]
	s_mov_b32 m0, s30
	s_nop 0
	global_load_lds_dwordx4 v70, s[98:99]
	s_mov_b32 m0, s31
	s_nop 0
	global_load_lds_dwordx4 v64, s[100:101]
	s_mov_b32 m0, s34
	s_nop 0
	global_load_lds_dwordx4 v66, s[100:101]
	s_mov_b32 m0, s35
	s_nop 0
	global_load_lds_dwordx4 v68, s[100:101]
	ds_read_b128 v[118:121], v111 offset:49152
	s_mov_b32 m0, s29
	s_nop 0
	global_load_lds_dwordx4 v70, s[100:101]
	s_add_u32 s98, s98, 0x80
	s_addc_u32 s99, s99, 0
	s_add_u32 s100, s100, 0x80
	s_addc_u32 s101, s101, 0
	ds_read_b128 v[122:125], v110 offset:32768
	ds_read_b128 v[126:129], v110 offset:36864
	s_waitcnt lgkmcnt(0)
	v_mfma_f32_32x32x16_bf16 v[32:47], v[118:121], v[122:125], v[32:47]
	s_mov_b32 m0, s70
	v_mfma_f32_32x32x16_bf16 v[0:15], v[118:121], v[126:129], v[0:15]
	ds_read_b128 v[118:121], v111 offset:53248
	s_waitcnt lgkmcnt(0)
	v_mfma_f32_32x32x16_bf16 v[48:63], v[118:121], v[122:125], v[48:63]
	v_mfma_f32_32x32x16_bf16 v[16:31], v[118:121], v[126:129], v[16:31]
	ds_read_b128 v[118:121], v113 offset:49152
	ds_read_b128 v[122:125], v112 offset:32768
	ds_read_b128 v[126:129], v112 offset:36864
	s_waitcnt lgkmcnt(0)
	v_mfma_f32_32x32x16_bf16 v[32:47], v[118:121], v[122:125], v[32:47]
	v_mfma_f32_32x32x16_bf16 v[0:15], v[118:121], v[126:129], v[0:15]
	ds_read_b128 v[118:121], v113 offset:53248
	s_waitcnt lgkmcnt(0)
	v_mfma_f32_32x32x16_bf16 v[48:63], v[118:121], v[122:125], v[48:63]
	v_mfma_f32_32x32x16_bf16 v[16:31], v[118:121], v[126:129], v[16:31]
	ds_read_b128 v[118:121], v115 offset:49152
	ds_read_b128 v[122:125], v114 offset:32768
	ds_read_b128 v[126:129], v114 offset:36864
	s_waitcnt lgkmcnt(0)
	v_mfma_f32_32x32x16_bf16 v[32:47], v[118:121], v[122:125], v[32:47]
	v_mfma_f32_32x32x16_bf16 v[0:15], v[118:121], v[126:129], v[0:15]
	ds_read_b128 v[118:121], v115 offset:53248
	s_waitcnt lgkmcnt(0)
	v_mfma_f32_32x32x16_bf16 v[48:63], v[118:121], v[122:125], v[48:63]
	v_mfma_f32_32x32x16_bf16 v[16:31], v[118:121], v[126:129], v[16:31]
	ds_read_b128 v[118:121], v117 offset:49152
	ds_read_b128 v[122:125], v116 offset:32768
	ds_read_b128 v[126:129], v116 offset:36864
	s_waitcnt lgkmcnt(0)
	v_mfma_f32_32x32x16_bf16 v[32:47], v[118:121], v[122:125], v[32:47]
	v_mfma_f32_32x32x16_bf16 v[0:15], v[118:121], v[126:129], v[0:15]
	ds_read_b128 v[118:121], v117 offset:53248
	s_waitcnt vmcnt(0)
	s_waitcnt vmcnt(0) lgkmcnt(0)
	s_barrier
	global_load_lds_dwordx4 v64, s[98:99]
	s_mov_b32 m0, s71
	v_mfma_f32_32x32x16_bf16 v[48:63], v[118:121], v[122:125], v[48:63]
	global_load_lds_dwordx4 v66, s[98:99]
	s_mov_b32 m0, s72
	s_nop 0
	global_load_lds_dwordx4 v68, s[98:99]
	s_mov_b32 m0, s73
	v_mfma_f32_32x32x16_bf16 v[16:31], v[118:121], v[126:129], v[16:31]
	global_load_lds_dwordx4 v70, s[98:99]
	s_mov_b32 m0, s78
	s_nop 0
	global_load_lds_dwordx4 v64, s[100:101]
	s_mov_b32 m0, s79
	s_nop 0
	global_load_lds_dwordx4 v66, s[100:101]
	ds_read_b128 v[76:79], v111 offset:16384
	s_mov_b32 m0, s80
	s_nop 0
	global_load_lds_dwordx4 v68, s[100:101]
	s_mov_b32 m0, s81
	ds_read_b128 v[84:87], v110
	global_load_lds_dwordx4 v70, s[100:101]
	ds_read_b128 v[80:83], v110 offset:4096
	s_waitcnt lgkmcnt(0)
	v_mfma_f32_32x32x16_bf16 v[32:47], v[76:79], v[84:87], v[32:47]
	v_mfma_f32_32x32x16_bf16 v[0:15], v[76:79], v[80:83], v[0:15]
	ds_read_b128 v[76:79], v111 offset:20480
	s_waitcnt lgkmcnt(0)
	v_mfma_f32_32x32x16_bf16 v[48:63], v[76:79], v[84:87], v[48:63]
	v_mfma_f32_32x32x16_bf16 v[16:31], v[76:79], v[80:83], v[16:31]
	ds_read_b128 v[76:79], v113 offset:16384
	ds_read_b128 v[80:83], v112
	ds_read_b128 v[84:87], v112 offset:4096
	s_waitcnt lgkmcnt(0)
	v_mfma_f32_32x32x16_bf16 v[32:47], v[76:79], v[80:83], v[32:47]
	v_mfma_f32_32x32x16_bf16 v[0:15], v[76:79], v[84:87], v[0:15]
	ds_read_b128 v[76:79], v113 offset:20480
	s_waitcnt lgkmcnt(0)
	v_mfma_f32_32x32x16_bf16 v[48:63], v[76:79], v[80:83], v[48:63]
	v_mfma_f32_32x32x16_bf16 v[16:31], v[76:79], v[84:87], v[16:31]
	ds_read_b128 v[76:79], v115 offset:16384
	ds_read_b128 v[80:83], v114
	ds_read_b128 v[84:87], v114 offset:4096
	s_waitcnt lgkmcnt(0)
	v_mfma_f32_32x32x16_bf16 v[32:47], v[76:79], v[80:83], v[32:47]
	v_mfma_f32_32x32x16_bf16 v[0:15], v[76:79], v[84:87], v[0:15]
	ds_read_b128 v[76:79], v115 offset:20480
	s_waitcnt lgkmcnt(0)
	v_mfma_f32_32x32x16_bf16 v[48:63], v[76:79], v[80:83], v[48:63]
	v_mfma_f32_32x32x16_bf16 v[16:31], v[76:79], v[84:87], v[16:31]
	ds_read_b128 v[76:79], v117 offset:16384
	ds_read_b128 v[80:83], v116
	ds_read_b128 v[84:87], v116 offset:4096
	s_waitcnt lgkmcnt(0)
	v_mfma_f32_32x32x16_bf16 v[32:47], v[76:79], v[80:83], v[32:47]
	v_mfma_f32_32x32x16_bf16 v[0:15], v[76:79], v[84:87], v[0:15]
	ds_read_b128 v[76:79], v117 offset:20480
	s_waitcnt vmcnt(0)
	s_waitcnt vmcnt(0) lgkmcnt(0)
	s_barrier
	v_mfma_f32_32x32x16_bf16 v[48:63], v[76:79], v[80:83], v[48:63]
	v_mfma_f32_32x32x16_bf16 v[16:31], v[76:79], v[84:87], v[16:31]
	ds_read_b128 v[76:79], v111 offset:49152
	ds_read_b128 v[80:83], v110 offset:32768
	ds_read_b128 v[84:87], v110 offset:36864
	s_waitcnt lgkmcnt(1)
	v_mfma_f32_32x32x16_bf16 v[32:47], v[76:79], v[80:83], v[32:47]
	s_waitcnt lgkmcnt(0)
	v_mfma_f32_32x32x16_bf16 v[0:15], v[76:79], v[84:87], v[0:15]
	ds_read_b128 v[76:79], v111 offset:53248
	s_waitcnt lgkmcnt(0)
	v_mfma_f32_32x32x16_bf16 v[48:63], v[76:79], v[80:83], v[48:63]
	v_mfma_f32_32x32x16_bf16 v[16:31], v[76:79], v[84:87], v[16:31]
	ds_read_b128 v[76:79], v113 offset:49152
	ds_read_b128 v[80:83], v112 offset:32768
	ds_read_b128 v[84:87], v112 offset:36864
	s_waitcnt lgkmcnt(1)
	v_mfma_f32_32x32x16_bf16 v[32:47], v[76:79], v[80:83], v[32:47]
	s_waitcnt lgkmcnt(0)
	v_mfma_f32_32x32x16_bf16 v[0:15], v[76:79], v[84:87], v[0:15]
	ds_read_b128 v[76:79], v113 offset:53248
	s_waitcnt lgkmcnt(0)
	v_mfma_f32_32x32x16_bf16 v[48:63], v[76:79], v[80:83], v[48:63]
	v_mfma_f32_32x32x16_bf16 v[16:31], v[76:79], v[84:87], v[16:31]
	ds_read_b128 v[76:79], v115 offset:49152
	ds_read_b128 v[80:83], v114 offset:32768
	ds_read_b128 v[84:87], v114 offset:36864
	s_waitcnt lgkmcnt(1)
	v_mfma_f32_32x32x16_bf16 v[32:47], v[76:79], v[80:83], v[32:47]
	s_waitcnt lgkmcnt(0)
	v_mfma_f32_32x32x16_bf16 v[0:15], v[76:79], v[84:87], v[0:15]
	ds_read_b128 v[76:79], v115 offset:53248
	s_waitcnt lgkmcnt(0)
	v_mfma_f32_32x32x16_bf16 v[48:63], v[76:79], v[80:83], v[48:63]
	v_mfma_f32_32x32x16_bf16 v[16:31], v[76:79], v[84:87], v[16:31]
	ds_read_b128 v[76:79], v117 offset:49152
	ds_read_b128 v[80:83], v116 offset:32768
	ds_read_b128 v[84:87], v116 offset:36864
	ds_read_b128 v[88:91], v117 offset:53248
	s_waitcnt vmcnt(0)
	s_waitcnt lgkmcnt(0)
	s_barrier
	v_mfma_f32_32x32x16_bf16 v[32:47], v[76:79], v[80:83], v[32:47]
	v_mfma_f32_32x32x16_bf16 v[0:15], v[76:79], v[84:87], v[0:15]
	v_add_u32_e32 v78, s10, v93
	v_lshlrev_b32_e32 v72, 8, v78
	v_and_b32_e32 v72, 0x1fdf00, v72
	v_lshl_add_u64 v[76:77], v[74:75], 0, v[72:73]
	s_cmp_gt_i32 s69, 15
	s_cbranch_scc1 .Lrope1_nopf
	global_load_dwordx4 v[160:163], v[76:77], off offset:128
	global_load_dwordx4 v[164:167], v[76:77], off
	global_load_dwordx4 v[168:171], v[76:77], off offset:160
	global_load_dwordx4 v[172:175], v[76:77], off offset:32
	global_load_dwordx4 v[176:179], v[76:77], off offset:192
	global_load_dwordx4 v[180:183], v[76:77], off offset:64
	global_load_dwordx4 v[184:187], v[76:77], off offset:224
	global_load_dwordx4 v[188:191], v[76:77], off offset:96
	v_or_b32_e32 v224, 32, v78
	v_lshlrev_b32_e32 v224, 8, v224
	v_and_b32_e32 v224, 0x1fff00, v224
	v_mov_b32_e32 v225, 0
	v_lshl_add_u64 v[224:225], v[74:75], 0, v[224:225]
	global_load_dwordx4 v[192:195], v[224:225], off offset:128
	global_load_dwordx4 v[196:199], v[224:225], off
	global_load_dwordx4 v[200:203], v[224:225], off offset:160
	global_load_dwordx4 v[204:207], v[224:225], off offset:32
	global_load_dwordx4 v[208:211], v[224:225], off offset:192
	global_load_dwordx4 v[212:215], v[224:225], off offset:64
	global_load_dwordx4 v[216:219], v[224:225], off offset:224
	global_load_dwordx4 v[220:223], v[224:225], off offset:96
.Lrope1_nopf:
	v_mfma_f32_32x32x16_bf16 v[48:63], v[88:91], v[80:83], v[48:63]
	v_mfma_f32_32x32x16_bf16 v[16:31], v[88:91], v[84:87], v[16:31]
	s_cmp_gt_i32 s69, 15
	s_cbranch_scc1 .LBB0_123
	s_waitcnt vmcnt(15)
	s_nop 6
	v_pk_mul_f32 v[88:89], v[50:51], v[162:163]
	v_pk_mul_f32 v[90:91], v[48:49], v[160:161]
	v_pk_mul_f32 v[162:163], v[34:35], v[162:163]
	v_pk_mul_f32 v[160:161], v[32:33], v[160:161]
	s_waitcnt vmcnt(14)
	v_pk_fma_f32 v[34:35], v[34:35], v[166:167], v[88:89] neg_lo:[0,0,1] neg_hi:[0,0,1]
	v_pk_fma_f32 v[32:33], v[32:33], v[164:165], v[90:91] neg_lo:[0,0,1] neg_hi:[0,0,1]
	v_pk_fma_f32 v[50:51], v[50:51], v[166:167], v[162:163]
	v_pk_fma_f32 v[48:49], v[48:49], v[164:165], v[160:161]
.LBB0_123:
	v_cndmask_b32_e64 v72, 0, 1, vcc
	v_cmp_ne_u32_e64 s[10:11], 1, v72
	s_andn2_b64 vcc, exec, vcc
	s_cbranch_vccnz .LBB0_125
	s_waitcnt vmcnt(13)
	s_nop 2
	v_pk_mul_f32 v[88:89], v[54:55], v[170:171]
	v_pk_mul_f32 v[90:91], v[52:53], v[168:169]
	v_pk_mul_f32 v[170:171], v[38:39], v[170:171]
	v_pk_mul_f32 v[168:169], v[36:37], v[168:169]
	s_waitcnt vmcnt(12)
	v_pk_fma_f32 v[38:39], v[38:39], v[174:175], v[88:89] neg_lo:[0,0,1] neg_hi:[0,0,1]
	v_pk_fma_f32 v[36:37], v[36:37], v[172:173], v[90:91] neg_lo:[0,0,1] neg_hi:[0,0,1]
	v_pk_fma_f32 v[54:55], v[54:55], v[174:175], v[170:171]
	v_pk_fma_f32 v[52:53], v[52:53], v[172:173], v[168:169]
.LBB0_125:
	v_readlane_b32 s72, v245, 37
	v_readlane_b32 s86, v245, 51
	v_readlane_b32 s87, v245, 52
	v_cvt_pk_bf16_f32 v80, v32, v33
	v_cvt_pk_bf16_f32 v81, v34, v35
	v_add_u32_e32 v32, s14, v94
	v_mov_b64_e32 v[34:35], s[86:87]
	v_cvt_pk_bf16_f32 v48, v48, v49
	v_cvt_pk_bf16_f32 v49, v50, v51
	v_mad_i64_i32 v[34:35], s[14:15], v78, s57, v[34:35]
	v_cvt_pk_bf16_f32 v82, v36, v37
	v_cvt_pk_bf16_f32 v83, v38, v39
	v_cvt_pk_bf16_f32 v50, v52, v53
	v_cvt_pk_bf16_f32 v51, v54, v55
	v_ashrrev_i32_e32 v33, 31, v32
	v_permlane32_swap_b32_e32 v80, v82
	v_permlane32_swap_b32_e32 v81, v83
	v_permlane32_swap_b32_e32 v48, v50
	v_permlane32_swap_b32_e32 v49, v51
	v_lshl_add_u64 v[34:35], v[32:33], 1, v[34:35]
	s_and_b64 vcc, exec, s[10:11]
	v_readlane_b32 s73, v245, 38
	v_readlane_b32 s74, v245, 39
	v_readlane_b32 s75, v245, 40
	v_readlane_b32 s76, v245, 41
	v_readlane_b32 s77, v245, 42
	v_readlane_b32 s78, v245, 43
	v_readlane_b32 s79, v245, 44
	v_readlane_b32 s80, v245, 45
	v_readlane_b32 s81, v245, 46
	v_readlane_b32 s82, v245, 47
	v_readlane_b32 s83, v245, 48
	v_readlane_b32 s84, v245, 49
	v_readlane_b32 s85, v245, 50
	global_store_dwordx4 v[34:35], v[80:83], off
	global_store_dwordx4 v[34:35], v[48:51], off offset:64
	s_cbranch_vccnz .LBB0_127
	s_waitcnt vmcnt(13)
	v_pk_mul_f32 v[52:53], v[58:59], v[178:179]
	v_pk_mul_f32 v[54:55], v[56:57], v[176:177]
	v_pk_mul_f32 v[178:179], v[42:43], v[178:179]
	v_pk_mul_f32 v[176:177], v[40:41], v[176:177]
	s_waitcnt vmcnt(12)
	v_pk_fma_f32 v[42:43], v[42:43], v[182:183], v[52:53] neg_lo:[0,0,1] neg_hi:[0,0,1]
	v_pk_fma_f32 v[40:41], v[40:41], v[180:181], v[54:55] neg_lo:[0,0,1] neg_hi:[0,0,1]
	v_pk_fma_f32 v[58:59], v[58:59], v[182:183], v[178:179]
	v_pk_fma_f32 v[56:57], v[56:57], v[180:181], v[176:177]
.LBB0_127:
	s_and_b64 vcc, exec, s[10:11]
	s_cbranch_vccnz .LBB0_129
	s_waitcnt vmcnt(11)
	v_pk_mul_f32 v[52:53], v[62:63], v[186:187]
	v_pk_mul_f32 v[54:55], v[60:61], v[184:185]
	v_pk_mul_f32 v[186:187], v[46:47], v[186:187]
	v_pk_mul_f32 v[184:185], v[44:45], v[184:185]
	s_waitcnt vmcnt(10)
	v_pk_fma_f32 v[46:47], v[46:47], v[190:191], v[52:53] neg_lo:[0,0,1] neg_hi:[0,0,1]
	v_pk_fma_f32 v[44:45], v[44:45], v[188:189], v[54:55] neg_lo:[0,0,1] neg_hi:[0,0,1]
	v_pk_fma_f32 v[62:63], v[62:63], v[190:191], v[186:187]
	v_pk_fma_f32 v[60:61], v[60:61], v[188:189], v[184:185]
.LBB0_129:
	v_cvt_pk_bf16_f32 v36, v40, v41
	v_cvt_pk_bf16_f32 v37, v42, v43
	v_cvt_pk_bf16_f32 v38, v44, v45
	v_cvt_pk_bf16_f32 v39, v46, v47
	v_cvt_pk_bf16_f32 v40, v56, v57
	v_cvt_pk_bf16_f32 v41, v58, v59
	v_cvt_pk_bf16_f32 v42, v60, v61
	v_cvt_pk_bf16_f32 v43, v62, v63
	v_permlane32_swap_b32_e32 v36, v38
	v_permlane32_swap_b32_e32 v37, v39
	v_permlane32_swap_b32_e32 v40, v42
	v_permlane32_swap_b32_e32 v41, v43
	global_store_dwordx4 v[34:35], v[36:39], off offset:32
	global_store_dwordx4 v[34:35], v[40:43], off offset:96
	s_and_b64 vcc, exec, s[10:11]
	v_or_b32_e32 v36, 32, v78
	v_lshlrev_b32_e32 v34, 8, v36
	v_and_b32_e32 v72, 0x1fff00, v34
	v_lshl_add_u64 v[34:35], v[74:75], 0, v[72:73]
	s_cbranch_vccnz .LBB0_131
	s_waitcnt vmcnt(11)
	v_pk_mul_f32 v[46:47], v[18:19], v[194:195]
	v_pk_mul_f32 v[48:49], v[16:17], v[192:193]
	v_pk_mul_f32 v[194:195], v[2:3], v[194:195]
	v_pk_mul_f32 v[192:193], v[0:1], v[192:193]
	s_waitcnt vmcnt(10)
	v_pk_fma_f32 v[2:3], v[2:3], v[198:199], v[46:47] neg_lo:[0,0,1] neg_hi:[0,0,1]
	v_pk_fma_f32 v[0:1], v[0:1], v[196:197], v[48:49] neg_lo:[0,0,1] neg_hi:[0,0,1]
	v_pk_fma_f32 v[18:19], v[18:19], v[198:199], v[194:195]
	v_pk_fma_f32 v[16:17], v[16:17], v[196:197], v[192:193]
.LBB0_131:
	s_and_b64 vcc, exec, s[10:11]
	s_cbranch_vccnz .LBB0_133
	s_waitcnt vmcnt(9)
	v_pk_mul_f32 v[46:47], v[22:23], v[202:203]
	v_pk_mul_f32 v[48:49], v[20:21], v[200:201]
	v_pk_mul_f32 v[202:203], v[6:7], v[202:203]
	v_pk_mul_f32 v[200:201], v[4:5], v[200:201]
	s_waitcnt vmcnt(8)
	v_pk_fma_f32 v[6:7], v[6:7], v[206:207], v[46:47] neg_lo:[0,0,1] neg_hi:[0,0,1]
	v_pk_fma_f32 v[4:5], v[4:5], v[204:205], v[48:49] neg_lo:[0,0,1] neg_hi:[0,0,1]
	v_pk_fma_f32 v[22:23], v[22:23], v[206:207], v[202:203]
	v_pk_fma_f32 v[20:21], v[20:21], v[204:205], v[200:201]
.LBB0_133:
	v_readlane_b32 s72, v245, 37
	v_readlane_b32 s86, v245, 51
	v_readlane_b32 s87, v245, 52
	v_cvt_pk_bf16_f32 v38, v0, v1
	v_cvt_pk_bf16_f32 v39, v2, v3
	v_mov_b64_e32 v[0:1], s[86:87]
	v_cvt_pk_bf16_f32 v2, v16, v17
	v_cvt_pk_bf16_f32 v3, v18, v19
	v_mad_i64_i32 v[0:1], s[14:15], v36, s57, v[0:1]
	v_cvt_pk_bf16_f32 v40, v4, v5
	v_cvt_pk_bf16_f32 v41, v6, v7
	v_cvt_pk_bf16_f32 v4, v20, v21
	v_cvt_pk_bf16_f32 v5, v22, v23
	v_permlane32_swap_b32_e32 v38, v40
	v_permlane32_swap_b32_e32 v39, v41
	v_permlane32_swap_b32_e32 v2, v4
	v_permlane32_swap_b32_e32 v3, v5
	v_lshl_add_u64 v[0:1], v[32:33], 1, v[0:1]
	s_and_b64 vcc, exec, s[10:11]
	v_readlane_b32 s73, v245, 38
	v_readlane_b32 s74, v245, 39
	v_readlane_b32 s75, v245, 40
	v_readlane_b32 s76, v245, 41
	v_readlane_b32 s77, v245, 42
	v_readlane_b32 s78, v245, 43
	v_readlane_b32 s79, v245, 44
	v_readlane_b32 s80, v245, 45
	v_readlane_b32 s81, v245, 46
	v_readlane_b32 s82, v245, 47
	v_readlane_b32 s83, v245, 48
	v_readlane_b32 s84, v245, 49
	v_readlane_b32 s85, v245, 50
	global_store_dwordx4 v[0:1], v[38:41], off
	global_store_dwordx4 v[0:1], v[2:5], off offset:64
	s_cbranch_vccnz .LBB0_135
	s_waitcnt vmcnt(9)
	v_pk_mul_f32 v[6:7], v[26:27], v[210:211]
	v_pk_mul_f32 v[20:21], v[24:25], v[208:209]
	v_pk_mul_f32 v[210:211], v[10:11], v[210:211]
	v_pk_mul_f32 v[208:209], v[8:9], v[208:209]
	s_waitcnt vmcnt(8)
	v_pk_fma_f32 v[6:7], v[10:11], v[214:215], v[6:7] neg_lo:[0,0,1] neg_hi:[0,0,1]
	v_pk_fma_f32 v[8:9], v[8:9], v[212:213], v[20:21] neg_lo:[0,0,1] neg_hi:[0,0,1]
	v_pk_fma_f32 v[26:27], v[26:27], v[214:215], v[210:211]
	v_pk_fma_f32 v[24:25], v[24:25], v[212:213], v[208:209]
	v_mov_b32_e32 v10, v6
	v_mov_b32_e32 v11, v7
.LBB0_135:
	s_and_b64 vcc, exec, s[10:11]
	s_cbranch_vccnz .LBB0_120
	s_waitcnt vmcnt(7)
	v_pk_mul_f32 v[6:7], v[30:31], v[218:219]
	v_pk_mul_f32 v[20:21], v[28:29], v[216:217]
	v_pk_mul_f32 v[218:219], v[14:15], v[218:219]
	v_pk_mul_f32 v[216:217], v[12:13], v[216:217]
	s_waitcnt vmcnt(6)
	v_pk_fma_f32 v[6:7], v[14:15], v[222:223], v[6:7] neg_lo:[0,0,1] neg_hi:[0,0,1]
	v_pk_fma_f32 v[12:13], v[12:13], v[220:221], v[20:21] neg_lo:[0,0,1] neg_hi:[0,0,1]
	v_pk_fma_f32 v[30:31], v[30:31], v[222:223], v[218:219]
	v_pk_fma_f32 v[28:29], v[28:29], v[220:221], v[216:217]
	v_mov_b32_e32 v14, v6
	v_mov_b32_e32 v15, v7
	s_branch .LBB0_120
